# v13 + neighbourhood-attention masked tiles: per-element column masks folded once per phase into a per-lane bit word, applied with v_bfe_i32+v_bfi_b32 instead of re-reading spilled lane masks
# speedup vs baseline: 1.0047x; 1.0047x over previous
.LBB0_179:
	s_and_b64 vcc, exec, s[0:1]
	s_cbranch_vccz .LBB0_299
	v_readlane_b32 s0, v254, 12
	s_cmpk_gt_i32 s0, 0x5ff
	s_cbranch_scc1 .LBB0_299
	s_mov_b32 s32, 0
	v_ashrrev_i32_e32 v2, 31, v146
	v_add_u32_e32 v147, 0x100, v146
	v_lshrrev_b32_e32 v2, 29, v2
	v_ashrrev_i32_e32 v4, 31, v147
	v_add_u32_e32 v2, v146, v2
	v_lshrrev_b32_e32 v4, 29, v4
	v_writelane_b32 v254, s96, 15
	v_ashrrev_i32_e32 v5, 1, v146
	s_movk_i32 s0, 0xffe0
	v_ashrrev_i32_e32 v114, 3, v2
	v_add_u32_e32 v4, v147, v4
	v_writelane_b32 v254, s97, 16
	v_bfi_b32 v113, s0, v5, v146
	v_ashrrev_i32_e32 v115, 31, v114
	v_ashrrev_i32_e32 v120, 3, v4
	s_movk_i32 s0, 0x90
	v_writelane_b32 v254, s94, 17
	v_lshlrev_b64 v[116:117], 10, v[114:115]
	v_ashrrev_i32_e32 v121, 31, v120
	v_ashrrev_i32_e32 v128, 3, v146
	v_ashrrev_i32_e32 v130, 3, v147
	v_mul_lo_u32 v115, v114, s0
	v_mul_lo_u32 v127, v120, s0
	s_movk_i32 s0, 0x88
	v_writelane_b32 v254, s95, 18
	v_lshlrev_b64 v[122:123], 10, v[120:121]
	v_mul_lo_u32 v202, v128, s0
	v_mul_lo_u32 v203, v130, s0
	s_mov_b64 s[0:1], 0x20000
	v_writelane_b32 v254, s92, 19
	v_and_b32_e32 v3, 31, v146
	v_lshl_add_u64 v[136:137], v[116:117], 0, s[0:1]
	v_lshl_add_u64 v[138:139], v[122:123], 0, s[0:1]
	s_mov_b64 s[0:1], 0x30000
	v_writelane_b32 v254, s93, 20
	v_lshl_add_u64 v[140:141], v[116:117], 0, s[0:1]
	v_lshl_add_u64 v[142:143], v[122:123], 0, s[0:1]
	s_movk_i32 s0, 0x1d1
	v_and_or_b32 v11, v5, 32, v3
	v_writelane_b32 v254, s2, 21
	s_waitcnt vmcnt(0)
	v_bfe_u32 v0, v146, 5, 1
	v_cmp_gt_i32_e64 s[0:1], s0, v146
	v_sub_u32_e64 v11, v11, 8 clamp
	v_lshlrev_b32_e32 v112, 3, v0
	v_lshlrev_b32_e32 v204, 4, v0
	v_lshlrev_b32_e32 v0, 2, v0
	v_writelane_b32 v254, s0, 22
	v_min_u32_e32 v11, 48, v11
	v_or_b32_e32 v14, 1, v0
	v_writelane_b32 v254, s1, 23
	v_cmp_ge_u32_e64 s[0:1], v0, v11
	v_and_b32_e32 v2, -8, v2
	v_sub_u32_e32 v2, v146, v2
	v_writelane_b32 v254, s0, 24
	v_lshlrev_b32_e32 v118, 3, v2
	v_lshlrev_b32_e32 v121, 4, v2
	v_writelane_b32 v254, s1, 25
	v_cmp_ge_u32_e64 s[0:1], v14, v11
	v_or_b32_e32 v14, 2, v0
	v_lshlrev_b32_e32 v2, 4, v146
	v_writelane_b32 v254, s0, 26
	v_and_b32_e32 v131, 0x70, v2
	v_or_b32_e32 v2, 8, v0
	v_writelane_b32 v254, s1, 27
	v_cmp_ge_u32_e64 s[0:1], v14, v11
	v_or_b32_e32 v14, 3, v0
	v_and_b32_e32 v4, -8, v4
	v_writelane_b32 v254, s0, 28
	v_sub_u32_e32 v4, v147, v4
	v_lshlrev_b32_e32 v124, 3, v4
	v_writelane_b32 v254, s1, 29
	v_cmp_ge_u32_e64 s[0:1], v14, v11
	v_or_b32_e32 v14, 9, v0
	v_lshlrev_b32_e32 v129, 4, v4
	v_writelane_b32 v254, s0, 30
	v_or_b32_e32 v4, 16, v0
	v_add_u32_e32 v13, 16, v11
	v_writelane_b32 v254, s1, 31
	v_cmp_ge_u32_e64 s[0:1], v2, v11
	v_lshlrev_b32_e32 v6, 3, v146
	v_and_b32_e32 v126, 56, v6
	v_writelane_b32 v254, s0, 32
	v_or_b32_e32 v6, 24, v0
	v_or_b32_e32 v9, 32, v0
	v_writelane_b32 v254, s1, 33
	v_cmp_ge_u32_e64 s[0:1], v14, v11
	v_or_b32_e32 v14, 10, v0
	v_or_b32_e32 v10, 40, v0
	v_writelane_b32 v254, s0, 34
	v_cmp_ge_u32_e64 s[8:9], v10, v11
	s_movk_i32 s2, 0xff
	v_writelane_b32 v254, s1, 35
	v_cmp_ge_u32_e64 s[0:1], v14, v11
	v_or_b32_e32 v14, 11, v0
	s_add_u32 s92, s62, 0x7af5000
	v_writelane_b32 v254, s0, 36
	s_addc_u32 s93, s63, 0
	s_add_u32 s76, s62, 0xaaf5000
	v_writelane_b32 v254, s1, 37
	v_cmp_ge_u32_e64 s[0:1], v14, v11
	v_or_b32_e32 v14, 17, v0
	s_addc_u32 s77, s63, 0
	v_writelane_b32 v254, s0, 38
	s_add_u32 s78, s62, 0xc4f5000
	s_addc_u32 s79, s63, 0
	v_writelane_b32 v254, s1, 39
	v_cmp_ge_u32_e64 s[0:1], v4, v11
	s_add_u32 s83, s62, 0xccf5000
	s_addc_u32 s85, s63, 0
	v_writelane_b32 v254, s0, 40
	s_add_u32 s86, s62, 0x92f5000
	s_load_dword s90, s[46:47], 0x0
	v_writelane_b32 v254, s1, 41
	v_cmp_lt_u32_e64 s[0:1], v0, v11
	s_addc_u32 s87, s63, 0
	s_add_u32 s88, s62, 0x14f5000
	v_writelane_b32 v254, s0, 42
	v_mul_u32_u24_e32 v205, 0x90, v3
	v_mul_u32_u24_e32 v232, 0x88, v3
	v_writelane_b32 v254, s1, 43
	v_cmp_ge_u32_e64 s[0:1], v14, v11
	v_lshlrev_b32_e32 v3, 2, v3
	v_lshlrev_b32_e32 v5, 2, v5
	v_writelane_b32 v254, s0, 44
	s_addc_u32 s89, s63, 0
	v_sub_u32_e32 v3, v204, v3
	v_writelane_b32 v254, s1, 45
	v_cmp_lt_u32_e64 s[0:1], v14, v13
	v_or_b32_e32 v14, 18, v0
	v_and_b32_e32 v5, 0x80, v5
	v_writelane_b32 v254, s0, 46
	v_sub_u32_e32 v7, v204, v112
	v_or_b32_e32 v12, 48, v0
	v_writelane_b32 v254, s1, 47
	v_cmp_ge_u32_e64 s[0:1], v14, v11
	v_or_b32_e32 v8, 56, v0
	v_lshlrev_b32_e32 v236, 2, v146
	v_writelane_b32 v254, s0, 48
	v_sub_u32_e32 v3, v3, v5
	v_ashrrev_i32_e32 v119, 31, v118
	v_writelane_b32 v254, s1, 49
	v_cmp_lt_u32_e64 s[0:1], v14, v13
	v_or_b32_e32 v14, 19, v0
	v_ashrrev_i32_e32 v125, 31, v124
	v_writelane_b32 v254, s0, 50
	v_lshl_add_u64 v[132:133], v[116:117], 0, s[56:57]
	v_lshl_add_u64 v[134:135], v[122:123], 0, s[56:57]
	v_writelane_b32 v254, s1, 51
	v_cmp_ge_u32_e64 s[0:1], v14, v11
	v_ashrrev_i32_e32 v233, 7, v146
	v_cmp_lt_u32_e64 s[10:11], v10, v13
	v_writelane_b32 v254, s0, 52
	v_cmp_lt_u32_e64 s[24:25], v12, v13
	v_cmp_lt_u32_e64 s[34:35], v8, v13
	v_writelane_b32 v254, s1, 53
	v_cmp_lt_u32_e64 s[0:1], v14, v13
	v_or_b32_e32 v14, 25, v0
	v_add_u32_e32 v237, 0xb000, v236
	v_writelane_b32 v254, s0, 54
	v_add_u32_e32 v238, 0xafc0, v3
	v_lshlrev_b32_e32 v144, 1, v0
	v_writelane_b32 v254, s1, 55
	v_cmp_ge_u32_e64 s[0:1], v6, v11
	v_lshlrev_b32_e32 v148, 1, v2
	v_lshlrev_b32_e32 v150, 1, v4
	v_writelane_b32 v254, s0, 56
	v_lshlrev_b32_e32 v152, 1, v6
	v_lshlrev_b32_e32 v154, 1, v10
	v_writelane_b32 v254, s1, 57
	v_cmp_lt_u32_e64 s[0:1], v6, v13
	v_lshlrev_b32_e32 v156, 1, v12
	v_lshlrev_b32_e32 v158, 1, v8
	v_writelane_b32 v254, s0, 58
	v_add_u32_e32 v239, v7, v232
	s_nop 0
	v_writelane_b32 v254, s1, 59
	v_cmp_ge_u32_e64 s[0:1], v14, v11
	s_nop 1
	v_writelane_b32 v254, s0, 60
	s_nop 1
	v_writelane_b32 v254, s1, 61
	v_cmp_lt_u32_e64 s[0:1], v14, v13
	v_or_b32_e32 v14, 26, v0
	s_nop 0
	v_writelane_b32 v254, s0, 62
	s_nop 1
	v_writelane_b32 v254, s1, 63
	v_cmp_ge_u32_e64 s[0:1], v14, v11
	v_readlane_b32 s72, v254, 12
	s_mov_b32 s50, s72
	v_writelane_b32 v255, s0, 0
	s_nop 1
	v_writelane_b32 v255, s1, 1
	v_cmp_lt_u32_e64 s[0:1], v14, v13
	v_or_b32_e32 v14, 27, v0
	s_nop 0
	v_writelane_b32 v255, s0, 2
	s_nop 1
	v_writelane_b32 v255, s1, 3
	v_cmp_ge_u32_e64 s[0:1], v14, v11
	s_nop 1
	v_writelane_b32 v255, s0, 4
	s_nop 1
	v_writelane_b32 v255, s1, 5
	v_cmp_lt_u32_e64 s[0:1], v14, v13
	s_nop 1
	v_writelane_b32 v255, s0, 6
	s_nop 1
	v_writelane_b32 v255, s1, 7
	v_cmp_ge_u32_e64 s[0:1], v9, v11
	s_nop 1
	v_writelane_b32 v255, s0, 8
	s_nop 1
	v_writelane_b32 v255, s1, 9
	v_cmp_lt_u32_e64 s[0:1], v9, v13
	v_or_b32_e32 v9, 33, v0
	v_cmp_lt_u32_e64 s[94:95], v9, v13
	v_writelane_b32 v255, s0, 10
	s_nop 1
	v_writelane_b32 v255, s1, 11
	v_cmp_ge_u32_e64 s[0:1], v9, v11
	v_or_b32_e32 v9, 34, v0
	v_cmp_ge_u32_e64 s[96:97], v9, v11
	v_cmp_lt_u32_e64 s[40:41], v9, v13
	v_or_b32_e32 v9, 35, v0
	v_cmp_ge_u32_e64 s[4:5], v9, v11
	v_cmp_lt_u32_e64 s[6:7], v9, v13
	v_or_b32_e32 v9, 41, v0
	v_cmp_ge_u32_e64 s[12:13], v9, v11
	v_cmp_lt_u32_e64 s[14:15], v9, v13
	v_or_b32_e32 v9, 42, v0
	v_cmp_ge_u32_e64 s[16:17], v9, v11
	v_cmp_lt_u32_e64 s[18:19], v9, v13
	v_or_b32_e32 v9, 43, v0
	v_cmp_ge_u32_e64 s[20:21], v9, v11
	v_cmp_lt_u32_e64 s[22:23], v9, v13
	v_or_b32_e32 v9, 49, v0
	v_cmp_lt_u32_e64 s[26:27], v9, v13
	v_or_b32_e32 v9, 50, v0
	v_cmp_lt_u32_e64 s[28:29], v9, v13
	v_or_b32_e32 v9, 51, v0
	v_cmp_lt_u32_e64 s[30:31], v9, v13
	v_or_b32_e32 v9, 57, v0
	v_writelane_b32 v255, s0, 12
	v_cmp_lt_u32_e64 s[36:37], v9, v13
	v_or_b32_e32 v9, 58, v0
	v_writelane_b32 v255, s1, 13
	v_cmp_lt_u32_e64 s[0:1], v9, v13
	v_or_b32_e32 v9, 59, v0
	v_cmp_lt_u32_e64 s[38:39], v9, v13
	v_max_i32_e32 v9, 0xd1, v146
	v_sub_u32_e32 v9, v9, v146
	v_add_u32_e32 v9, 0xff, v9
	v_lshrrev_b32_e32 v11, 8, v9
	v_add_u32_e32 v11, 1, v11
	v_cmp_lt_u32_e64 s[2:3], s2, v9
	v_and_b32_e32 v234, 0x1fffffe, v11
	v_lshl_add_u32 v235, v234, 8, v146
	v_writelane_b32 v255, s2, 14
	s_nop 1
	v_writelane_b32 v255, s3, 15
	v_cmp_ne_u32_e64 s[2:3], v11, v234
	s_nop 1
	v_writelane_b32 v255, s2, 16
	s_nop 1
	v_writelane_b32 v255, s3, 17
	v_writelane_b32 v255, s76, 18
	v_writelane_b32 v255, s77, 19
	v_writelane_b32 v255, s78, 20
	v_writelane_b32 v255, s79, 21
	v_writelane_b32 v255, s83, 22
	v_writelane_b32 v255, s85, 23
	v_writelane_b32 v255, s86, 24
	v_writelane_b32 v255, s87, 25
	v_writelane_b32 v255, s88, 26
	v_writelane_b32 v255, s89, 27
	s_waitcnt lgkmcnt(0)
	v_writelane_b32 v255, s90, 28
	s_branch .LBB0_185

.LBB0_224:
	s_and_saveexec_b64 s[46:47], s[42:43]
	s_cbranch_execz .LBB0_294
	s_bitcmp1_b32 s70, 0
	s_cselect_b32 s42, 0x4600, 0
	v_or_b32_e32 v0, s42, v204
	v_add_u32_e32 v0, v0, v205
	ds_read_b128 v[2:5], v0
	ds_read_b128 v[6:9], v0 offset:4608
	s_setprio 1
	ds_read_b128 v[10:13], v0 offset:32
	ds_read_b128 v[176:179], v0 offset:4640
	s_waitcnt vmcnt(3) lgkmcnt(3)
	v_mfma_f32_32x32x16_bf16 v[64:79], v[2:5], v[80:83], 0
	s_waitcnt lgkmcnt(2)
	v_mfma_f32_32x32x16_bf16 v[48:63], v[6:9], v[80:83], 0
	ds_read_b128 v[2:5], v0 offset:64
	ds_read_b128 v[6:9], v0 offset:4672
	s_waitcnt vmcnt(2) lgkmcnt(3)
	v_mfma_f32_32x32x16_bf16 v[64:79], v[10:13], v[84:87], v[64:79]
	s_waitcnt lgkmcnt(2)
	v_mfma_f32_32x32x16_bf16 v[48:63], v[176:179], v[84:87], v[48:63]
	ds_read_b128 v[10:13], v0 offset:96
	ds_read_b128 v[176:179], v0 offset:4704
	s_waitcnt vmcnt(1) lgkmcnt(3)
	v_mfma_f32_32x32x16_bf16 v[64:79], v[2:5], v[88:91], v[64:79]
	s_waitcnt lgkmcnt(2)
	v_mfma_f32_32x32x16_bf16 v[48:63], v[6:9], v[88:91], v[48:63]
	s_waitcnt vmcnt(0) lgkmcnt(1)
	v_mfma_f32_32x32x16_bf16 v[64:79], v[10:13], v[92:95], v[64:79]
	s_waitcnt lgkmcnt(0)
	v_mfma_f32_32x32x16_bf16 v[48:63], v[176:179], v[92:95], v[48:63]
	v_or_b32_e32 v0, s42, v112
	v_add_u32_e32 v0, v0, v232
	v_add_u32_e32 v155, 0x2000, v0
	v_add_u32_e32 v0, 0x3000, v0
	ds_read2_b64 v[2:5], v155 offset0:128 offset1:130
	ds_read2_b64 v[6:9], v0 offset0:160 offset1:162
	s_mov_b64 s[42:43], -1
	s_and_b64 vcc, exec, s[64:65]
	s_nop 2
	v_mov_b32_e32 v201, v63
	v_mov_b32_e32 v200, v62
	v_mov_b32_e32 v199, v61
	v_mov_b32_e32 v198, v60
	v_mov_b32_e32 v197, v59
	v_mov_b32_e32 v196, v58
	v_mov_b32_e32 v195, v57
	v_mov_b32_e32 v194, v56
	v_mov_b32_e32 v193, v55
	v_mov_b32_e32 v192, v54
	v_mov_b32_e32 v191, v53
	v_mov_b32_e32 v190, v52
	v_mov_b32_e32 v189, v51
	v_mov_b32_e32 v188, v50
	v_mov_b32_e32 v187, v49
	v_mov_b32_e32 v186, v48
	v_mov_b32_e32 v185, v79
	v_mov_b32_e32 v184, v78
	v_mov_b32_e32 v183, v77
	v_mov_b32_e32 v182, v76
	v_mov_b32_e32 v181, v75
	v_mov_b32_e32 v180, v74
	v_mov_b32_e32 v179, v73
	v_mov_b32_e32 v178, v72
	v_mov_b32_e32 v177, v71
	v_mov_b32_e32 v176, v70
	v_mov_b32_e32 v15, v69
	v_mov_b32_e32 v14, v68
	v_mov_b32_e32 v13, v67
	v_mov_b32_e32 v12, v66
	v_mov_b32_e32 v11, v65
	v_mov_b32_e32 v10, v64
	s_cbranch_vccz .LBB0_296
	s_add_i32 s42, s67, s70
	v_cmp_ge_i32_e32 vcc, s42, v145
	v_cmp_lt_i32_e64 s[42:43], s42, v149
	v_mov_b32_e32 v218, 0xff800000
	ds_read2_b32 v[10:11], v153 offset0:0 offset1:1
	ds_read2_b32 v[12:13], v153 offset0:2 offset1:3
	ds_read2_b32 v[14:15], v153 offset0:8 offset1:9
	ds_read2_b32 v[176:177], v153 offset0:10 offset1:11
	ds_read2_b32 v[178:179], v153 offset0:16 offset1:17
	ds_read2_b32 v[180:181], v153 offset0:18 offset1:19
	ds_read2_b32 v[182:183], v153 offset0:24 offset1:25
	ds_read2_b32 v[184:185], v153 offset0:26 offset1:27
	ds_read2_b32 v[186:187], v153 offset0:32 offset1:33
	ds_read2_b32 v[188:189], v153 offset0:34 offset1:35
	ds_read2_b32 v[190:191], v153 offset0:40 offset1:41
	ds_read2_b32 v[192:193], v153 offset0:42 offset1:43
	ds_read2_b32 v[194:195], v153 offset0:48 offset1:49
	ds_read2_b32 v[196:197], v153 offset0:50 offset1:51
	ds_read2_b32 v[198:199], v153 offset0:56 offset1:57
	ds_read2_b32 v[200:201], v153 offset0:58 offset1:59
	s_waitcnt lgkmcnt(0)
	v_fmac_f32_e32 v10, 0x3e38aa3b, v64
	v_fmac_f32_e32 v11, 0x3e38aa3b, v65
	v_fmac_f32_e32 v12, 0x3e38aa3b, v66
	v_fmac_f32_e32 v13, 0x3e38aa3b, v67
	v_fmac_f32_e32 v14, 0x3e38aa3b, v68
	v_fmac_f32_e32 v15, 0x3e38aa3b, v69
	v_fmac_f32_e32 v176, 0x3e38aa3b, v70
	v_fmac_f32_e32 v177, 0x3e38aa3b, v71
	v_fmac_f32_e32 v178, 0x3e38aa3b, v72
	v_fmac_f32_e32 v179, 0x3e38aa3b, v73
	v_fmac_f32_e32 v180, 0x3e38aa3b, v74
	v_fmac_f32_e32 v181, 0x3e38aa3b, v75
	v_fmac_f32_e32 v182, 0x3e38aa3b, v76
	v_fmac_f32_e32 v183, 0x3e38aa3b, v77
	v_fmac_f32_e32 v184, 0x3e38aa3b, v78
	v_fmac_f32_e32 v185, 0x3e38aa3b, v79
	v_fmac_f32_e32 v186, 0x3e38aa3b, v48
	v_fmac_f32_e32 v187, 0x3e38aa3b, v49
	v_fmac_f32_e32 v188, 0x3e38aa3b, v50
	v_fmac_f32_e32 v189, 0x3e38aa3b, v51
	v_fmac_f32_e32 v190, 0x3e38aa3b, v52
	v_fmac_f32_e32 v191, 0x3e38aa3b, v53
	v_fmac_f32_e32 v192, 0x3e38aa3b, v54
	v_fmac_f32_e32 v193, 0x3e38aa3b, v55
	v_fmac_f32_e32 v194, 0x3e38aa3b, v56
	v_fmac_f32_e32 v195, 0x3e38aa3b, v57
	v_fmac_f32_e32 v196, 0x3e38aa3b, v58
	v_fmac_f32_e32 v197, 0x3e38aa3b, v59
	v_fmac_f32_e32 v198, 0x3e38aa3b, v60
	v_fmac_f32_e32 v199, 0x3e38aa3b, v61
	v_fmac_f32_e32 v200, 0x3e38aa3b, v62
	v_fmac_f32_e32 v201, 0x3e38aa3b, v63
	s_and_b64 s[42:43], vcc, s[42:43]
	s_cmp_lg_u32 s32, 0
	s_cbranch_scc1 .Lna_fast
	s_mov_b64 s[100:101], s[42:43]
	s_mov_b64 s[42:43], -1
	v_mov_b32_e32 v221, 0
	v_readlane_b32 s64, v254, 24
	v_readlane_b32 s65, v254, 25
	s_and_b64 s[74:75], s[42:43], s[64:65]
	v_cndmask_b32_e64 v240, 0, 1, s[74:75]
	v_lshl_or_b32 v221, v240, 0, v221
	v_readlane_b32 s64, v254, 26
	v_readlane_b32 s65, v254, 27
	s_and_b64 s[74:75], s[42:43], s[64:65]
	v_cndmask_b32_e64 v240, 0, 1, s[74:75]
	v_lshl_or_b32 v221, v240, 1, v221
	v_readlane_b32 s64, v254, 28
	v_readlane_b32 s65, v254, 29
	s_and_b64 s[74:75], s[42:43], s[64:65]
	v_cndmask_b32_e64 v240, 0, 1, s[74:75]
	v_lshl_or_b32 v221, v240, 2, v221
	v_readlane_b32 s64, v254, 30
	v_readlane_b32 s65, v254, 31
	s_and_b64 s[74:75], s[42:43], s[64:65]
	v_cndmask_b32_e64 v240, 0, 1, s[74:75]
	v_lshl_or_b32 v221, v240, 3, v221
	v_readlane_b32 s64, v254, 32
	v_readlane_b32 s65, v254, 33
	s_and_b64 s[74:75], s[42:43], s[64:65]
	v_cndmask_b32_e64 v240, 0, 1, s[74:75]
	v_lshl_or_b32 v221, v240, 4, v221
	v_readlane_b32 s64, v254, 34
	v_readlane_b32 s65, v254, 35
	s_and_b64 s[74:75], s[42:43], s[64:65]
	v_cndmask_b32_e64 v240, 0, 1, s[74:75]
	v_lshl_or_b32 v221, v240, 5, v221
	v_readlane_b32 s64, v254, 36
	v_readlane_b32 s65, v254, 37
	s_and_b64 s[74:75], s[42:43], s[64:65]
	v_cndmask_b32_e64 v240, 0, 1, s[74:75]
	v_lshl_or_b32 v221, v240, 6, v221
	v_readlane_b32 s64, v254, 38
	v_readlane_b32 s65, v254, 39
	s_and_b64 s[74:75], s[42:43], s[64:65]
	v_cndmask_b32_e64 v240, 0, 1, s[74:75]
	v_lshl_or_b32 v221, v240, 7, v221
	v_readlane_b32 s64, v254, 40
	v_readlane_b32 s65, v254, 41
	v_readlane_b32 s74, v254, 42
	s_and_b64 s[64:65], s[42:43], s[64:65]
	v_readlane_b32 s75, v254, 43
	s_and_b64 s[74:75], s[64:65], s[74:75]
	v_cndmask_b32_e64 v240, 0, 1, s[74:75]
	v_lshl_or_b32 v221, v240, 8, v221
	v_readlane_b32 s64, v254, 44
	v_readlane_b32 s65, v254, 45
	v_readlane_b32 s74, v254, 46
	s_and_b64 s[64:65], s[42:43], s[64:65]
	v_readlane_b32 s75, v254, 47
	s_and_b64 s[74:75], s[64:65], s[74:75]
	v_cndmask_b32_e64 v240, 0, 1, s[74:75]
	v_lshl_or_b32 v221, v240, 9, v221
	v_readlane_b32 s64, v254, 48
	v_readlane_b32 s65, v254, 49
	v_readlane_b32 s74, v254, 50
	s_and_b64 s[64:65], s[42:43], s[64:65]
	v_readlane_b32 s75, v254, 51
	s_and_b64 s[74:75], s[64:65], s[74:75]
	v_cndmask_b32_e64 v240, 0, 1, s[74:75]
	v_lshl_or_b32 v221, v240, 10, v221
	v_readlane_b32 s64, v254, 52
	v_readlane_b32 s65, v254, 53
	v_readlane_b32 s74, v254, 54
	s_and_b64 s[64:65], s[42:43], s[64:65]
	v_readlane_b32 s75, v254, 55
	s_and_b64 s[74:75], s[64:65], s[74:75]
	v_cndmask_b32_e64 v240, 0, 1, s[74:75]
	v_lshl_or_b32 v221, v240, 11, v221
	v_readlane_b32 s64, v254, 56
	v_readlane_b32 s65, v254, 57
	v_readlane_b32 s74, v254, 58
	s_and_b64 s[64:65], s[42:43], s[64:65]
	v_readlane_b32 s75, v254, 59
	s_and_b64 s[74:75], s[64:65], s[74:75]
	v_cndmask_b32_e64 v240, 0, 1, s[74:75]
	v_lshl_or_b32 v221, v240, 12, v221
	v_readlane_b32 s64, v254, 60
	v_readlane_b32 s65, v254, 61
	v_readlane_b32 s74, v254, 62
	s_and_b64 s[64:65], s[42:43], s[64:65]
	v_readlane_b32 s75, v254, 63
	s_and_b64 s[74:75], s[64:65], s[74:75]
	v_cndmask_b32_e64 v240, 0, 1, s[74:75]
	v_lshl_or_b32 v221, v240, 13, v221
	v_readlane_b32 s64, v255, 0
	v_readlane_b32 s65, v255, 1
	v_readlane_b32 s74, v255, 2
	s_and_b64 s[64:65], s[42:43], s[64:65]
	v_readlane_b32 s75, v255, 3
	s_and_b64 s[74:75], s[64:65], s[74:75]
	v_cndmask_b32_e64 v240, 0, 1, s[74:75]
	v_lshl_or_b32 v221, v240, 14, v221
	v_readlane_b32 s64, v255, 4
	v_readlane_b32 s65, v255, 5
	v_readlane_b32 s74, v255, 6
	s_and_b64 s[64:65], s[42:43], s[64:65]
	v_readlane_b32 s75, v255, 7
	s_and_b64 s[74:75], s[64:65], s[74:75]
	v_cndmask_b32_e64 v240, 0, 1, s[74:75]
	v_lshl_or_b32 v221, v240, 15, v221
	v_readlane_b32 s64, v255, 8
	v_readlane_b32 s65, v255, 9
	v_readlane_b32 s74, v255, 10
	s_and_b64 s[64:65], s[42:43], s[64:65]
	v_readlane_b32 s75, v255, 11
	s_and_b64 s[74:75], s[64:65], s[74:75]
	v_cndmask_b32_e64 v240, 0, 1, s[74:75]
	v_lshl_or_b32 v221, v240, 16, v221
	v_readlane_b32 s64, v255, 12
	v_readlane_b32 s65, v255, 13
	s_and_b64 s[64:65], s[42:43], s[64:65]
	s_and_b64 s[74:75], s[64:65], s[94:95]
	v_cndmask_b32_e64 v240, 0, 1, s[74:75]
	v_lshl_or_b32 v221, v240, 17, v221
	s_and_b64 s[64:65], s[42:43], s[96:97]
	s_and_b64 s[74:75], s[64:65], s[40:41]
	v_cndmask_b32_e64 v240, 0, 1, s[74:75]
	v_lshl_or_b32 v221, v240, 18, v221
	s_and_b64 s[64:65], s[42:43], s[4:5]
	s_and_b64 s[74:75], s[64:65], s[6:7]
	v_cndmask_b32_e64 v240, 0, 1, s[74:75]
	v_lshl_or_b32 v221, v240, 19, v221
	s_and_b64 s[64:65], s[42:43], s[8:9]
	s_and_b64 s[74:75], s[64:65], s[10:11]
	v_cndmask_b32_e64 v240, 0, 1, s[74:75]
	v_lshl_or_b32 v221, v240, 20, v221
	s_and_b64 s[64:65], s[42:43], s[12:13]
	s_and_b64 s[74:75], s[64:65], s[14:15]
	v_cndmask_b32_e64 v240, 0, 1, s[74:75]
	v_lshl_or_b32 v221, v240, 21, v221
	s_and_b64 s[64:65], s[42:43], s[16:17]
	s_and_b64 s[74:75], s[64:65], s[18:19]
	v_cndmask_b32_e64 v240, 0, 1, s[74:75]
	v_lshl_or_b32 v221, v240, 22, v221
	s_and_b64 s[64:65], s[42:43], s[20:21]
	s_and_b64 s[74:75], s[64:65], s[22:23]
	v_cndmask_b32_e64 v240, 0, 1, s[74:75]
	v_lshl_or_b32 v221, v240, 23, v221
	s_and_b64 s[74:75], s[42:43], s[24:25]
	v_cndmask_b32_e64 v240, 0, 1, s[74:75]
	v_lshl_or_b32 v221, v240, 24, v221
	s_and_b64 s[74:75], s[42:43], s[26:27]
	v_cndmask_b32_e64 v240, 0, 1, s[74:75]
	v_lshl_or_b32 v221, v240, 25, v221
	s_and_b64 s[74:75], s[42:43], s[28:29]
	v_cndmask_b32_e64 v240, 0, 1, s[74:75]
	v_lshl_or_b32 v221, v240, 26, v221
	s_and_b64 s[74:75], s[42:43], s[30:31]
	v_cndmask_b32_e64 v240, 0, 1, s[74:75]
	v_lshl_or_b32 v221, v240, 27, v221
	s_and_b64 s[74:75], s[42:43], s[34:35]
	v_cndmask_b32_e64 v240, 0, 1, s[74:75]
	v_lshl_or_b32 v221, v240, 28, v221
	s_and_b64 s[74:75], s[42:43], s[36:37]
	v_cndmask_b32_e64 v240, 0, 1, s[74:75]
	v_lshl_or_b32 v221, v240, 29, v221
	s_and_b64 s[74:75], s[42:43], s[0:1]
	v_cndmask_b32_e64 v240, 0, 1, s[74:75]
	v_lshl_or_b32 v221, v240, 30, v221
	s_and_b64 s[64:65], s[42:43], s[38:39]
	v_cndmask_b32_e64 v240, 0, 1, s[64:65]
	v_lshl_or_b32 v221, v240, 31, v221
	s_mov_b64 s[42:43], s[100:101]
	s_mov_b32 s32, 1
.Lna_fast:
	v_cndmask_b32_e64 v240, 0, v221, s[42:43]
	v_bfe_i32 v241, v240, 0, 1
	v_bfi_b32 v10, v241, v10, v218
	v_bfe_i32 v242, v240, 1, 1
	v_bfi_b32 v11, v242, v11, v218
	v_bfe_i32 v243, v240, 2, 1
	v_bfi_b32 v12, v243, v12, v218
	v_bfe_i32 v244, v240, 3, 1
	v_bfi_b32 v13, v244, v13, v218
	v_bfe_i32 v241, v240, 4, 1
	v_bfi_b32 v14, v241, v14, v218
	v_bfe_i32 v242, v240, 5, 1
	v_bfi_b32 v15, v242, v15, v218
	v_bfe_i32 v243, v240, 6, 1
	v_bfi_b32 v176, v243, v176, v218
	v_bfe_i32 v244, v240, 7, 1
	v_bfi_b32 v177, v244, v177, v218
	v_bfe_i32 v241, v240, 8, 1
	v_bfi_b32 v178, v241, v178, v218
	v_bfe_i32 v242, v240, 9, 1
	v_bfi_b32 v179, v242, v179, v218
	v_bfe_i32 v243, v240, 10, 1
	v_bfi_b32 v180, v243, v180, v218
	v_bfe_i32 v244, v240, 11, 1
	v_bfi_b32 v181, v244, v181, v218
	v_bfe_i32 v241, v240, 12, 1
	v_bfi_b32 v182, v241, v182, v218
	v_bfe_i32 v242, v240, 13, 1
	v_bfi_b32 v183, v242, v183, v218
	v_bfe_i32 v243, v240, 14, 1
	v_bfi_b32 v184, v243, v184, v218
	v_bfe_i32 v244, v240, 15, 1
	v_bfi_b32 v185, v244, v185, v218
	v_bfe_i32 v241, v240, 16, 1
	v_bfi_b32 v186, v241, v186, v218
	v_bfe_i32 v242, v240, 17, 1
	v_bfi_b32 v187, v242, v187, v218
	v_bfe_i32 v243, v240, 18, 1
	v_bfi_b32 v188, v243, v188, v218
	v_bfe_i32 v244, v240, 19, 1
	v_bfi_b32 v189, v244, v189, v218
	v_bfe_i32 v241, v240, 20, 1
	v_bfi_b32 v190, v241, v190, v218
	v_bfe_i32 v242, v240, 21, 1
	v_bfi_b32 v191, v242, v191, v218
	v_bfe_i32 v243, v240, 22, 1
	v_bfi_b32 v192, v243, v192, v218
	v_bfe_i32 v244, v240, 23, 1
	v_bfi_b32 v193, v244, v193, v218
	v_bfe_i32 v241, v240, 24, 1
	v_bfi_b32 v194, v241, v194, v218
	v_bfe_i32 v242, v240, 25, 1
	v_bfi_b32 v195, v242, v195, v218
	v_bfe_i32 v243, v240, 26, 1
	v_bfi_b32 v196, v243, v196, v218
	v_bfe_i32 v244, v240, 27, 1
	v_bfi_b32 v197, v244, v197, v218
	v_bfe_i32 v241, v240, 28, 1
	v_bfi_b32 v198, v241, v198, v218
	v_bfe_i32 v242, v240, 29, 1
	v_bfi_b32 v199, v242, v199, v218
	v_bfe_i32 v243, v240, 30, 1
	v_bfi_b32 v200, v243, v200, v218
	v_bfe_i32 v244, v240, 31, 1
	v_bfi_b32 v201, v244, v201, v218
	s_mov_b64 s[42:43], exec
	v_max3_f32 v157, v10, s55, v11
	v_max3_f32 v157, v157, v12, v13
	v_max3_f32 v157, v157, v14, v15
	v_max3_f32 v157, v157, v176, v177
	v_max3_f32 v157, v157, v178, v179
	v_max3_f32 v157, v157, v180, v181
	v_max3_f32 v157, v157, v182, v183
	v_max3_f32 v157, v157, v184, v185
	v_max3_f32 v157, v157, v186, v187
	v_max3_f32 v157, v157, v188, v189
	v_max3_f32 v157, v157, v190, v191
	v_max3_f32 v157, v157, v192, v193
	v_max3_f32 v157, v157, v194, v195
	v_max3_f32 v157, v157, v196, v197
	v_max3_f32 v157, v157, v198, v199
	v_max3_f32 v157, v157, v200, v201
	v_mov_b32_e32 v159, v157
	s_nop 1
	v_permlane32_swap_b32_e32 v157, v159
	v_max_f32_e32 v159, v159, v159
	v_max_f32_e32 v157, v157, v157
	v_max_f32_e32 v157, v157, v159
